# GU phases: tile order group height 8 instead of 16 (A panels of an XCD round fit its L2)
# speedup vs baseline: 1.0162x; 1.0048x over previous
.LBB0_179:
	s_cmp_lt_i32 s62, 2
	s_cselect_b64 s[6:7], -1, 0
	s_cmp_gt_i32 s61, 1
	s_cselect_b64 s[8:9], -1, 0
	s_and_b64 s[6:7], s[6:7], s[8:9]
	s_andn2_b64 vcc, exec, s[6:7]
	s_cbranch_vccnz .LBB0_248
	s_mov_b64 s[6:7], s[0:1]
	s_mov_b64 s[12:13], s[0:1]
	s_mov_b64 s[8:9], s[0:1]
	s_mov_b64 s[10:11], s[0:1]
	s_cmpk_gt_i32 s2, 0xaff
	v_readfirstlane_b32 s3, v192
	s_cbranch_scc1 .LBB0_194
	v_lshrrev_b32_e32 v0, 5, v192
	v_lshrrev_b32_e32 v2, 1, v192
	s_load_dwordx2 s[14:15], s[8:9], 0x100
	s_load_dwordx2 s[24:25], s[10:11], 0x100
	v_and_b32_e32 v0, 4, v0
	v_bfe_u32 v1, v192, 2, 2
	v_and_b32_e32 v11, 24, v2
	v_or3_b32 v0, v0, v1, v11
	v_lshlrev_b32_e32 v1, 4, v192
	v_add_u32_e32 v8, 0x2000, v1
	v_lshrrev_b32_e32 v2, 7, v8
	s_movk_i32 s8, 0xe0
	v_and_b32_e32 v4, 32, v192
	s_waitcnt lgkmcnt(0)
	s_add_u32 s17, s14, 0x16000000
	v_and_or_b32 v3, v2, s8, v0
	v_bitop3_b32 v9, v1, v4, 48 bitop3:0x6c
	v_and_b32_e32 v10, 64, v192
	v_bfe_u32 v12, v192, 2, 4
	s_movk_i32 s8, 0xf0
	s_addc_u32 s40, s15, 0
	v_or_b32_e32 v1, v9, v10
	v_and_or_b32 v2, v2, s8, v12
	s_add_u32 s41, s24, 0x1a600000
	v_lshl_or_b32 v130, v2, 11, v1
	v_lshrrev_b32_e32 v2, 3, v192
	s_movk_i32 s8, 0x60
	s_addc_u32 s42, s25, 0
	v_and_or_b32 v0, v2, s8, v0
	s_movk_i32 s8, 0x70
	s_ashr_i32 s44, s2, 31
	v_lshl_or_b32 v132, v0, 11, v1
	v_and_or_b32 v0, v2, s8, v12
	s_lshr_b32 s8, s44, 29
	s_add_i32 s8, s2, s8
	s_lshr_b32 s25, s3, 6
	s_ashr_i32 s9, s8, 3
	s_and_b32 s8, s8, -8
	s_lshr_b32 s24, s3, 8
	s_lshl_b32 s43, s25, 10
	s_sub_i32 s8, s2, s8
	s_cmp_lt_i32 s8, 0
	s_movk_i32 s45, 0x161
	s_cselect_b32 s10, s45, 0x160
	s_mul_i32 s8, s10, s8
	s_add_i32 s8, s8, s9
	s_mul_hi_i32 s9, s8, 0x2e8ba2e9
	s_lshr_b32 s10, s9, 31
	s_ashr_i32 s9, s9, 5
	s_add_i32 s9, s9, s10
	s_lshl_b32 s10, s9, 3
	s_mulk_i32 s9, 0xb0
	s_sub_i32 s8, s8, s9
	s_sext_i32_i16 s9, s8
	s_bfe_u32 s9, s9, 0x3001c
	s_add_i32 s9, s8, s9
	s_sext_i32_i16 s11, s9
	s_and_b32 s9, s9, 0xfff8
	s_sub_i32 s8, s8, s9
	s_sext_i32_i16 s8, s8
	s_lshr_b32 s16, s11, 3
	s_add_i32 s34, s10, s8
	s_ashr_i32 s35, s34, 31
	s_bfe_i64 s[10:11], s[16:17], 0x100000
	s_lshl_b64 s[8:9], s[34:35], 19
	s_lshl_b64 s[10:11], s[10:11], 19
	s_add_u32 s36, s41, s10
	s_addc_u32 s37, s42, s11
	s_add_i32 s35, s43, 0
	s_add_i32 m0, s35, 0x10000
	v_lshl_or_b32 v128, v3, 11, v1
	global_load_lds_dwordx4 v132, s[36:37]
	s_add_i32 m0, s35, 0x12000
	s_add_u32 s8, s17, s8
	v_lshl_or_b32 v134, v0, 11, v1
	global_load_lds_dwordx4 v128, s[36:37]
	s_addc_u32 s9, s40, s9
	s_mov_b32 m0, s35
	s_add_i32 s46, s35, 0x2000
	global_load_lds_dwordx4 v134, s[8:9]
	s_mov_b32 m0, s46
	s_add_u32 s10, s36, 0x40000
	global_load_lds_dwordx4 v130, s[8:9]
	s_addc_u32 s11, s37, 0
	s_add_i32 m0, s35, 0x14000
	v_mov_b32_e32 v133, 0
	global_load_lds_dwordx4 v132, s[10:11]
	s_add_i32 m0, s35, 0x16000
	v_mov_b32_e32 v129, v133
	global_load_lds_dwordx4 v128, s[10:11]
	s_add_u32 s10, s8, 0x40000
	s_addc_u32 s11, s9, 0
	s_add_i32 s47, s35, 0x4000
	s_mov_b32 m0, s47
	s_add_i32 s48, s35, 0x6000
	global_load_lds_dwordx4 v134, s[10:11]
	s_mov_b32 m0, s48
	v_mov_b32_e32 v135, v133
	global_load_lds_dwordx4 v130, s[10:11]
	s_load_dwordx2 s[10:11], s[6:7], 0x100
	s_load_dwordx2 s[14:15], s[12:13], 0x100
	v_mov_b32_e32 v131, v133
	s_mov_b32 s49, 0
	v_lshl_add_u64 v[6:7], s[36:37], 0, v[132:133]
	v_lshl_add_u64 v[4:5], s[36:37], 0, v[128:129]
	v_lshl_add_u64 v[2:3], s[8:9], 0, v[134:135]
	s_cmp_lg_u32 s24, 1
	v_lshl_add_u64 v[0:1], s[8:9], 0, v[130:131]
	s_cbranch_scc1 .LBB0_183
	s_barrier

.LBB0_185:
	s_add_i32 s49, s49, 1
	s_mul_i32 s6, s49, s53
	s_mul_hi_u32 s7, s49, s54
	s_add_i32 s7, s7, s6
	s_mul_i32 s6, s49, s54
	s_add_u32 s28, s6, s2
	s_addc_u32 s29, s7, s44
	v_cmp_gt_i64_e64 s[6:7], s[28:29], v[142:143]
	s_and_b64 vcc, exec, s[6:7]
	s_cbranch_vccnz .LBB0_187
	s_ashr_i32 s24, s28, 31
	s_lshr_b32 s24, s24, 29
	s_add_i32 s24, s28, s24
	s_ashr_i32 s25, s24, 3
	s_and_b32 s24, s24, -8
	s_sub_i32 s24, s28, s24
	s_cmp_lt_i32 s24, 0
	s_cselect_b32 s26, s45, 0x160
	s_mul_i32 s24, s26, s24
	s_add_i32 s24, s24, s25
	s_mul_hi_i32 s25, s24, 0x2e8ba2e9
	s_lshr_b32 s26, s25, 31
	s_ashr_i32 s25, s25, 5
	s_add_i32 s25, s25, s26
	s_lshl_b32 s26, s25, 3
	s_sub_i32 s27, 0x80, s26
	s_min_i32 s27, s27, 8
	s_abs_i32 s30, s27
	v_cvt_f32_u32_e32 v0, s30
	s_sub_i32 s38, 0, s30
	s_mulk_i32 s25, 0xb0
	s_sub_i32 s25, s24, s25
	v_rcp_iflag_f32_e32 v0, v0
	s_abs_i32 s24, s25
	s_xor_b32 s31, s25, s27
	s_ashr_i32 s31, s31, 31
	v_mul_f32_e32 v0, 0x4f7ffffe, v0
	v_cvt_u32_f32_e32 v0, v0
	s_nop 0
	v_readfirstlane_b32 s39, v0
	s_mul_i32 s38, s38, s39
	s_mul_hi_u32 s38, s39, s38
	s_add_i32 s39, s39, s38
	s_mul_hi_u32 s38, s24, s39
	s_mul_i32 s39, s38, s30
	s_sub_i32 s24, s24, s39
	s_add_i32 s65, s38, 1
	s_sub_i32 s39, s24, s30
	s_cmp_ge_u32 s24, s30
	s_cselect_b32 s38, s65, s38
	s_cselect_b32 s24, s39, s24
	s_add_i32 s39, s38, 1
	s_cmp_ge_u32 s24, s30
	s_cselect_b32 s24, s39, s38
	s_xor_b32 s24, s24, s31
	s_sub_i32 s24, s24, s31
	s_mul_i32 s27, s24, s27
	s_sub_i32 s25, s25, s27
	s_add_i32 s26, s25, s26

.LBB0_895:
	s_cmp_lt_i32 s62, 9
	s_waitcnt lgkmcnt(0)
	s_cselect_b64 s[6:7], -1, 0
	s_cmp_gt_i32 s61, 8
	s_cselect_b64 s[8:9], -1, 0
	s_and_b64 s[6:7], s[6:7], s[8:9]
	s_andn2_b64 vcc, exec, s[6:7]
	s_cbranch_vccnz .LBB0_964
	s_mov_b64 s[6:7], s[0:1]
	s_mov_b64 s[12:13], s[0:1]
	s_mov_b64 s[8:9], s[0:1]
	s_mov_b64 s[10:11], s[0:1]
	s_cmpk_gt_i32 s2, 0xaff
	v_readfirstlane_b32 s3, v192
	s_cbranch_scc1 .LBB0_910
	v_lshrrev_b32_e32 v0, 5, v192
	v_lshrrev_b32_e32 v2, 1, v192
	s_load_dwordx2 s[14:15], s[8:9], 0x100
	s_load_dwordx2 s[24:25], s[10:11], 0x100
	v_and_b32_e32 v0, 4, v0
	v_bfe_u32 v1, v192, 2, 2
	v_and_b32_e32 v11, 24, v2
	v_or3_b32 v0, v0, v1, v11
	v_lshlrev_b32_e32 v1, 4, v192
	v_add_u32_e32 v8, 0x2000, v1
	v_lshrrev_b32_e32 v2, 7, v8
	s_movk_i32 s8, 0xe0
	v_and_b32_e32 v4, 32, v192
	s_waitcnt lgkmcnt(0)
	s_add_u32 s17, s14, 0x16000000
	v_and_or_b32 v3, v2, s8, v0
	v_bitop3_b32 v9, v1, v4, 48 bitop3:0x6c
	v_and_b32_e32 v10, 64, v192
	v_bfe_u32 v12, v192, 2, 4
	s_movk_i32 s8, 0xf0
	s_addc_u32 s40, s15, 0
	v_or_b32_e32 v1, v9, v10
	v_and_or_b32 v2, v2, s8, v12
	s_add_u32 s41, s24, 0x1b100000
	v_lshl_or_b32 v130, v2, 11, v1
	v_lshrrev_b32_e32 v2, 3, v192
	s_movk_i32 s8, 0x60
	s_addc_u32 s42, s25, 0
	v_and_or_b32 v0, v2, s8, v0
	s_movk_i32 s8, 0x70
	s_ashr_i32 s44, s2, 31
	v_lshl_or_b32 v132, v0, 11, v1
	v_and_or_b32 v0, v2, s8, v12
	s_lshr_b32 s8, s44, 29
	s_add_i32 s8, s2, s8
	s_lshr_b32 s25, s3, 6
	s_ashr_i32 s9, s8, 3
	s_and_b32 s8, s8, -8
	s_lshr_b32 s24, s3, 8
	s_lshl_b32 s43, s25, 10
	s_sub_i32 s8, s2, s8
	s_cmp_lt_i32 s8, 0
	s_movk_i32 s45, 0x161
	s_cselect_b32 s10, s45, 0x160
	s_mul_i32 s8, s10, s8
	s_add_i32 s8, s8, s9
	s_mul_hi_i32 s9, s8, 0x2e8ba2e9
	s_lshr_b32 s10, s9, 31
	s_ashr_i32 s9, s9, 5
	s_add_i32 s9, s9, s10
	s_lshl_b32 s10, s9, 3
	s_mulk_i32 s9, 0xb0
	s_sub_i32 s8, s8, s9
	s_sext_i32_i16 s9, s8
	s_bfe_u32 s9, s9, 0x3001c
	s_add_i32 s9, s8, s9
	s_sext_i32_i16 s11, s9
	s_and_b32 s9, s9, 0xfff8
	s_sub_i32 s8, s8, s9
	s_sext_i32_i16 s8, s8
	s_lshr_b32 s16, s11, 3
	s_add_i32 s34, s10, s8
	s_ashr_i32 s35, s34, 31
	s_bfe_i64 s[10:11], s[16:17], 0x100000
	s_lshl_b64 s[8:9], s[34:35], 19
	s_lshl_b64 s[10:11], s[10:11], 19
	s_add_u32 s36, s41, s10
	s_addc_u32 s37, s42, s11
	s_add_i32 s35, s43, 0
	s_add_i32 m0, s35, 0x10000
	v_lshl_or_b32 v128, v3, 11, v1
	global_load_lds_dwordx4 v132, s[36:37]
	s_add_i32 m0, s35, 0x12000
	s_add_u32 s8, s17, s8
	v_lshl_or_b32 v134, v0, 11, v1
	global_load_lds_dwordx4 v128, s[36:37]
	s_addc_u32 s9, s40, s9
	s_mov_b32 m0, s35
	s_add_i32 s46, s35, 0x2000
	global_load_lds_dwordx4 v134, s[8:9]
	s_mov_b32 m0, s46
	s_add_u32 s10, s36, 0x40000
	global_load_lds_dwordx4 v130, s[8:9]
	s_addc_u32 s11, s37, 0
	s_add_i32 m0, s35, 0x14000
	v_mov_b32_e32 v133, 0
	global_load_lds_dwordx4 v132, s[10:11]
	s_add_i32 m0, s35, 0x16000
	v_mov_b32_e32 v129, v133
	global_load_lds_dwordx4 v128, s[10:11]
	s_add_u32 s10, s8, 0x40000
	s_addc_u32 s11, s9, 0
	s_add_i32 s47, s35, 0x4000
	s_mov_b32 m0, s47
	s_add_i32 s48, s35, 0x6000
	global_load_lds_dwordx4 v134, s[10:11]
	s_mov_b32 m0, s48
	v_mov_b32_e32 v135, v133
	global_load_lds_dwordx4 v130, s[10:11]
	s_load_dwordx2 s[10:11], s[6:7], 0x100
	s_load_dwordx2 s[14:15], s[12:13], 0x100
	v_mov_b32_e32 v131, v133
	s_mov_b32 s49, 0
	v_lshl_add_u64 v[6:7], s[36:37], 0, v[132:133]
	v_lshl_add_u64 v[4:5], s[36:37], 0, v[128:129]
	v_lshl_add_u64 v[2:3], s[8:9], 0, v[134:135]
	s_cmp_lg_u32 s24, 1
	v_lshl_add_u64 v[0:1], s[8:9], 0, v[130:131]
	s_cbranch_scc1 .LBB0_899
	s_barrier

.LBB0_1061:
	s_cmp_lt_i32 s62, 11
	s_waitcnt lgkmcnt(0)
	s_cselect_b64 s[6:7], -1, 0
	s_cmp_gt_i32 s61, 10
	s_cselect_b64 s[8:9], -1, 0
	s_and_b64 s[6:7], s[6:7], s[8:9]
	s_andn2_b64 vcc, exec, s[6:7]
	s_cbranch_vccnz .LBB0_1130
	s_mov_b64 s[6:7], s[0:1]
	s_mov_b64 s[12:13], s[0:1]
	s_mov_b64 s[8:9], s[0:1]
	s_mov_b64 s[10:11], s[0:1]
	s_cmpk_gt_i32 s2, 0xaff
	v_readfirstlane_b32 s3, v192
	s_cbranch_scc1 .LBB0_1076
	v_lshrrev_b32_e32 v0, 5, v192
	v_lshrrev_b32_e32 v2, 1, v192
	s_load_dwordx2 s[14:15], s[8:9], 0x100
	s_load_dwordx2 s[24:25], s[10:11], 0x100
	v_and_b32_e32 v0, 4, v0
	v_bfe_u32 v1, v192, 2, 2
	v_and_b32_e32 v11, 24, v2
	v_or3_b32 v0, v0, v1, v11
	v_lshlrev_b32_e32 v1, 4, v192
	v_add_u32_e32 v8, 0x2000, v1
	v_lshrrev_b32_e32 v2, 7, v8
	s_movk_i32 s8, 0xe0
	v_and_b32_e32 v4, 32, v192
	s_waitcnt lgkmcnt(0)
	s_add_u32 s17, s14, 0x16000000
	v_and_or_b32 v3, v2, s8, v0
	v_bitop3_b32 v9, v1, v4, 48 bitop3:0x6c
	v_and_b32_e32 v10, 64, v192
	v_bfe_u32 v12, v192, 2, 4
	s_movk_i32 s8, 0xf0
	s_addc_u32 s40, s15, 0
	v_or_b32_e32 v1, v9, v10
	v_and_or_b32 v2, v2, s8, v12
	s_add_u32 s41, s24, 0x1bc00000
	v_lshl_or_b32 v130, v2, 11, v1
	v_lshrrev_b32_e32 v2, 3, v192
	s_movk_i32 s8, 0x60
	s_addc_u32 s42, s25, 0
	v_and_or_b32 v0, v2, s8, v0
	s_movk_i32 s8, 0x70
	s_ashr_i32 s44, s2, 31
	v_lshl_or_b32 v132, v0, 11, v1
	v_and_or_b32 v0, v2, s8, v12
	s_lshr_b32 s8, s44, 29
	s_add_i32 s8, s2, s8
	s_lshr_b32 s25, s3, 6
	s_ashr_i32 s9, s8, 3
	s_and_b32 s8, s8, -8
	s_lshr_b32 s24, s3, 8
	s_lshl_b32 s43, s25, 10
	s_sub_i32 s8, s2, s8
	s_cmp_lt_i32 s8, 0
	s_movk_i32 s45, 0x161
	s_cselect_b32 s10, s45, 0x160
	s_mul_i32 s8, s10, s8
	s_add_i32 s8, s8, s9
	s_mul_hi_i32 s9, s8, 0x2e8ba2e9
	s_lshr_b32 s10, s9, 31
	s_ashr_i32 s9, s9, 5
	s_add_i32 s9, s9, s10
	s_lshl_b32 s10, s9, 3
	s_mulk_i32 s9, 0xb0
	s_sub_i32 s8, s8, s9
	s_sext_i32_i16 s9, s8
	s_bfe_u32 s9, s9, 0x3001c
	s_add_i32 s9, s8, s9
	s_sext_i32_i16 s11, s9
	s_and_b32 s9, s9, 0xfff8
	s_sub_i32 s8, s8, s9
	s_sext_i32_i16 s8, s8
	s_lshr_b32 s16, s11, 3
	s_add_i32 s34, s10, s8
	s_ashr_i32 s35, s34, 31
	s_bfe_i64 s[10:11], s[16:17], 0x100000
	s_lshl_b64 s[8:9], s[34:35], 19
	s_lshl_b64 s[10:11], s[10:11], 19
	s_add_u32 s36, s41, s10
	s_addc_u32 s37, s42, s11
	s_add_i32 s35, s43, 0
	s_add_i32 m0, s35, 0x10000
	v_lshl_or_b32 v128, v3, 11, v1
	global_load_lds_dwordx4 v132, s[36:37]
	s_add_i32 m0, s35, 0x12000
	s_add_u32 s8, s17, s8
	v_lshl_or_b32 v134, v0, 11, v1
	global_load_lds_dwordx4 v128, s[36:37]
	s_addc_u32 s9, s40, s9
	s_mov_b32 m0, s35
	s_add_i32 s46, s35, 0x2000
	global_load_lds_dwordx4 v134, s[8:9]
	s_mov_b32 m0, s46
	s_add_u32 s10, s36, 0x40000
	global_load_lds_dwordx4 v130, s[8:9]
	s_addc_u32 s11, s37, 0
	s_add_i32 m0, s35, 0x14000
	v_mov_b32_e32 v133, 0
	global_load_lds_dwordx4 v132, s[10:11]
	s_add_i32 m0, s35, 0x16000
	v_mov_b32_e32 v129, v133
	global_load_lds_dwordx4 v128, s[10:11]
	s_add_u32 s10, s8, 0x40000
	s_addc_u32 s11, s9, 0
	s_add_i32 s47, s35, 0x4000
	s_mov_b32 m0, s47
	s_add_i32 s48, s35, 0x6000
	global_load_lds_dwordx4 v134, s[10:11]
	s_mov_b32 m0, s48
	v_mov_b32_e32 v135, v133
	global_load_lds_dwordx4 v130, s[10:11]
	s_load_dwordx2 s[10:11], s[6:7], 0x100
	s_load_dwordx2 s[14:15], s[12:13], 0x100
	v_mov_b32_e32 v131, v133
	s_mov_b32 s49, 0
	v_lshl_add_u64 v[6:7], s[36:37], 0, v[132:133]
	v_lshl_add_u64 v[4:5], s[36:37], 0, v[128:129]
	v_lshl_add_u64 v[2:3], s[8:9], 0, v[134:135]
	s_cmp_lg_u32 s24, 1
	v_lshl_add_u64 v[0:1], s[8:9], 0, v[130:131]
	s_cbranch_scc1 .LBB0_1065
	s_barrier

.LBB0_2777:
	s_cmp_lt_i32 s62, 18
	s_waitcnt lgkmcnt(0)
	s_cselect_b64 s[6:7], -1, 0
	s_cmp_gt_i32 s61, 17
	s_cselect_b64 s[8:9], -1, 0
	s_and_b64 s[6:7], s[6:7], s[8:9]
	s_andn2_b64 vcc, exec, s[6:7]
	s_cbranch_vccnz .LBB0_2846
	s_mov_b64 s[6:7], s[0:1]
	s_mov_b64 s[12:13], s[0:1]
	s_mov_b64 s[8:9], s[0:1]
	s_mov_b64 s[10:11], s[0:1]
	s_cmpk_gt_i32 s2, 0xaff
	v_readfirstlane_b32 s3, v192
	s_cbranch_scc1 .LBB0_2792
	v_lshrrev_b32_e32 v0, 5, v192
	v_lshrrev_b32_e32 v2, 1, v192
	s_load_dwordx2 s[14:15], s[8:9], 0x100
	s_load_dwordx2 s[24:25], s[10:11], 0x100
	v_and_b32_e32 v0, 4, v0
	v_bfe_u32 v1, v192, 2, 2
	v_and_b32_e32 v11, 24, v2
	v_or3_b32 v0, v0, v1, v11
	v_lshlrev_b32_e32 v1, 4, v192
	v_add_u32_e32 v8, 0x2000, v1
	v_lshrrev_b32_e32 v2, 7, v8
	s_movk_i32 s8, 0xe0
	v_and_b32_e32 v4, 32, v192
	s_waitcnt lgkmcnt(0)
	s_add_u32 s17, s14, 0x16000000
	v_and_or_b32 v3, v2, s8, v0
	v_bitop3_b32 v9, v1, v4, 48 bitop3:0x6c
	v_and_b32_e32 v10, 64, v192
	v_bfe_u32 v12, v192, 2, 4
	s_movk_i32 s8, 0xf0
	s_addc_u32 s40, s15, 0
	v_or_b32_e32 v1, v9, v10
	v_and_or_b32 v2, v2, s8, v12
	s_add_u32 s41, s24, 0x1c700000
	v_lshl_or_b32 v130, v2, 11, v1
	v_lshrrev_b32_e32 v2, 3, v192
	s_movk_i32 s8, 0x60
	s_addc_u32 s42, s25, 0
	v_and_or_b32 v0, v2, s8, v0
	s_movk_i32 s8, 0x70
	s_ashr_i32 s44, s2, 31
	v_lshl_or_b32 v132, v0, 11, v1
	v_and_or_b32 v0, v2, s8, v12
	s_lshr_b32 s8, s44, 29
	s_add_i32 s8, s2, s8
	s_lshr_b32 s25, s3, 6
	s_ashr_i32 s9, s8, 3
	s_and_b32 s8, s8, -8
	s_lshr_b32 s24, s3, 8
	s_lshl_b32 s43, s25, 10
	s_sub_i32 s8, s2, s8
	s_cmp_lt_i32 s8, 0
	s_movk_i32 s45, 0x161
	s_cselect_b32 s10, s45, 0x160
	s_mul_i32 s8, s10, s8
	s_add_i32 s8, s8, s9
	s_mul_hi_i32 s9, s8, 0x2e8ba2e9
	s_lshr_b32 s10, s9, 31
	s_ashr_i32 s9, s9, 5
	s_add_i32 s9, s9, s10
	s_lshl_b32 s10, s9, 3
	s_mulk_i32 s9, 0xb0
	s_sub_i32 s8, s8, s9
	s_sext_i32_i16 s9, s8
	s_bfe_u32 s9, s9, 0x3001c
	s_add_i32 s9, s8, s9
	s_sext_i32_i16 s11, s9
	s_and_b32 s9, s9, 0xfff8
	s_sub_i32 s8, s8, s9
	s_sext_i32_i16 s8, s8
	s_lshr_b32 s16, s11, 3
	s_add_i32 s34, s10, s8
	s_ashr_i32 s35, s34, 31
	s_bfe_i64 s[10:11], s[16:17], 0x100000
	s_lshl_b64 s[8:9], s[34:35], 19
	s_lshl_b64 s[10:11], s[10:11], 19
	s_add_u32 s36, s41, s10
	s_addc_u32 s37, s42, s11
	s_add_i32 s35, s43, 0
	s_add_i32 m0, s35, 0x10000
	v_lshl_or_b32 v128, v3, 11, v1
	global_load_lds_dwordx4 v132, s[36:37]
	s_add_i32 m0, s35, 0x12000
	s_add_u32 s8, s17, s8
	v_lshl_or_b32 v134, v0, 11, v1
	global_load_lds_dwordx4 v128, s[36:37]
	s_addc_u32 s9, s40, s9
	s_mov_b32 m0, s35
	s_add_i32 s46, s35, 0x2000
	global_load_lds_dwordx4 v134, s[8:9]
	s_mov_b32 m0, s46
	s_add_u32 s10, s36, 0x40000
	global_load_lds_dwordx4 v130, s[8:9]
	s_addc_u32 s11, s37, 0
	s_add_i32 m0, s35, 0x14000
	v_mov_b32_e32 v133, 0
	global_load_lds_dwordx4 v132, s[10:11]
	s_add_i32 m0, s35, 0x16000
	v_mov_b32_e32 v129, v133
	global_load_lds_dwordx4 v128, s[10:11]
	s_add_u32 s10, s8, 0x40000
	s_addc_u32 s11, s9, 0
	s_add_i32 s47, s35, 0x4000
	s_mov_b32 m0, s47
	s_add_i32 s48, s35, 0x6000
	global_load_lds_dwordx4 v134, s[10:11]
	s_mov_b32 m0, s48
	v_mov_b32_e32 v135, v133
	global_load_lds_dwordx4 v130, s[10:11]
	s_load_dwordx2 s[10:11], s[6:7], 0x100
	s_load_dwordx2 s[14:15], s[12:13], 0x100
	v_mov_b32_e32 v131, v133
	s_mov_b32 s49, 0
	v_lshl_add_u64 v[6:7], s[36:37], 0, v[132:133]
	v_lshl_add_u64 v[4:5], s[36:37], 0, v[128:129]
	v_lshl_add_u64 v[2:3], s[8:9], 0, v[134:135]
	s_cmp_lg_u32 s24, 1
	v_lshl_add_u64 v[0:1], s[8:9], 0, v[130:131]
	s_cbranch_scc1 .LBB0_2781
	s_barrier

.LBB0_2783:
	s_add_i32 s49, s49, 1
	s_mul_i32 s6, s49, s53
	s_mul_hi_u32 s7, s49, s54
	s_add_i32 s7, s7, s6
	s_mul_i32 s6, s49, s54
	s_add_u32 s28, s6, s2
	s_addc_u32 s29, s7, s44
	v_cmp_gt_i64_e64 s[6:7], s[28:29], v[142:143]
	s_and_b64 vcc, exec, s[6:7]
	s_cbranch_vccnz .LBB0_2785
	s_ashr_i32 s24, s28, 31
	s_lshr_b32 s24, s24, 29
	s_add_i32 s24, s28, s24
	s_ashr_i32 s25, s24, 3
	s_and_b32 s24, s24, -8
	s_sub_i32 s24, s28, s24
	s_cmp_lt_i32 s24, 0
	s_cselect_b32 s26, s45, 0x160
	s_mul_i32 s24, s26, s24
	s_add_i32 s24, s24, s25
	s_mul_hi_i32 s25, s24, 0x2e8ba2e9
	s_lshr_b32 s26, s25, 31
	s_ashr_i32 s25, s25, 5
	s_add_i32 s25, s25, s26
	s_lshl_b32 s26, s25, 3
	s_sub_i32 s27, 0x80, s26
	s_min_i32 s27, s27, 8
	s_abs_i32 s30, s27
	v_cvt_f32_u32_e32 v0, s30
	s_sub_i32 s38, 0, s30
	s_mulk_i32 s25, 0xb0
	s_sub_i32 s25, s24, s25
	v_rcp_iflag_f32_e32 v0, v0
	s_abs_i32 s24, s25
	s_xor_b32 s31, s25, s27
	s_ashr_i32 s31, s31, 31
	v_mul_f32_e32 v0, 0x4f7ffffe, v0
	v_cvt_u32_f32_e32 v0, v0
	s_nop 0
	v_readfirstlane_b32 s39, v0
	s_mul_i32 s38, s38, s39
	s_mul_hi_u32 s38, s39, s38
	s_add_i32 s39, s39, s38
	s_mul_hi_u32 s38, s24, s39
	s_mul_i32 s39, s38, s30
	s_sub_i32 s24, s24, s39
	s_add_i32 s64, s38, 1
	s_sub_i32 s39, s24, s30
	s_cmp_ge_u32 s24, s30
	s_cselect_b32 s38, s64, s38
	s_cselect_b32 s24, s39, s24
	s_add_i32 s39, s38, 1
	s_cmp_ge_u32 s24, s30
	s_cselect_b32 s24, s39, s38
	s_xor_b32 s24, s24, s31
	s_sub_i32 s24, s24, s31
	s_mul_i32 s27, s24, s27
	s_sub_i32 s25, s25, s27
	s_add_i32 s26, s25, s26
